# NSA importance pass: per-head cbuf accumulation reads batched (1 LDS round trip instead of 4)
# baseline (speedup 1.0000x reference)
; #define MFMA32(a, b, c) __builtin_amdgcn_mfma_f32_32x32x16_bf16((a), (b), (c), 0, 0, 0)
; DI float ex2(float x) { return __builtin_amdgcn_exp2f(x); }
; DI float xor32(float v) { return __shfl_xor(v, 32); }
; DI void task_nsa(const P& p, int layer, int task, bf16_t* sm, int dm) {
;     ...
;       float val[2][4];
; #pragma unroll
;       for (int st = 0; st < 2; ++st) {
;         f32x16 s;
; #pragma unroll
;         for (int i = 0; i < 16; ++i) s[i] = 0.f;
; #pragma unroll
;         for (int ks = 0; ks < 4; ++ks) {
;           bf16x8 kf = *(const bf16x8*)(Kl + (st * 32 + lr) * 72 + ks * 16 + lh * 8);
;           s = MFMA32(kf, q[ks], s);
;         }
;         float pq[4], pl[4], other[4];
; #pragma unroll
;         for (int g4 = 0; g4 < 4; ++g4) {
;           float sum = 0.f, last = 0.f;
; #pragma unroll
;           for (int e = 0; e < 4; ++e) {
;             const int cc = ct * 64 + st * 32 + 8 * g4 + 4 * lh + e;
;             const float pe = (16 * cc + 31 <= qp) ? ex2(s[4 * g4 + e] - m) * inv : 0.f;
;             sum += pe; last = pe;
;           }
;           pq[g4] = sum; pl[g4] = last;
;         }
; #pragma unroll
;         for (int g4 = 0; g4 < 4; ++g4) other[g4] = xor32(pl[g4]);
;         val[st][0] = pq[0] + (lh ? other[0] : carry);
;         val[st][1] = pq[1] + (lh ? other[1] : other[0]);
;         val[st][2] = pq[2] + (lh ? other[2] : other[1]);
;         val[st][3] = pq[3] + (lh ? other[3] : other[2]);
;         carry = other[3];
;       }
.LBB0_676:
	v_add3_u32 v35, s0, v27, v24
	s_waitcnt lgkmcnt(0)
	s_barrier
	ds_read_b128 v[0:3], v35
	ds_read_b128 v[36:39], v35 offset:32
	s_waitcnt lgkmcnt(1)
	v_mfma_f32_32x32x16_bf16 v[0:15], v[0:3], v[64:67], 0
	v_add_u32_e32 v29, 0xfffffc50, v26
	v_cmp_le_i32_e64 s[0:1], v29, v135
	v_add_u32_e32 v29, 0xfffffc60, v26
	s_waitcnt lgkmcnt(0)
	v_mfma_f32_32x32x16_bf16 v[0:15], v[36:39], v[68:71], v[0:15]
	ds_read_b128 v[36:39], v35 offset:64
	s_waitcnt lgkmcnt(0)
	v_mfma_f32_32x32x16_bf16 v[0:15], v[36:39], v[72:75], v[0:15]
	ds_read_b128 v[36:39], v35 offset:96
	s_waitcnt lgkmcnt(0)
	v_mfma_f32_32x32x16_bf16 v[0:15], v[36:39], v[76:79], v[0:15]
	ds_read_b128 v[38:41], v35 offset:4640
	s_nop 10
	v_sub_f32_e32 v0, v0, v33
	v_exp_f32_e32 v0, v0
	v_sub_f32_e32 v1, v1, v33
	v_exp_f32_e32 v1, v1
	v_sub_f32_e32 v2, v2, v33
	v_fma_f32 v0, v32, v0, 0
	v_exp_f32_e32 v2, v2
	v_cndmask_b32_e64 v0, 0, v0, s[0:1]
	v_mul_f32_e32 v1, v32, v1
	v_cmp_le_i32_e64 s[0:1], v29, v135
	v_mul_f32_e32 v2, v32, v2
	s_nop 0
	v_cndmask_b32_e64 v1, 0, v1, s[0:1]
	v_add_f32_e32 v0, v1, v0
	v_add_u32_e32 v1, 0xfffffc70, v26
	v_cmp_le_i32_e64 s[0:1], v1, v135
	s_nop 1
	v_cndmask_b32_e64 v1, 0, v2, s[0:1]
	v_sub_f32_e32 v2, v3, v33
	v_exp_f32_e32 v2, v2
	v_sub_f32_e32 v3, v4, v33
	v_exp_f32_e32 v3, v3
	v_add_f32_e32 v0, v1, v0
	v_add_u32_e32 v1, 0xfffffc80, v26
	v_sub_f32_e32 v4, v5, v33
	v_mul_f32_e32 v2, v32, v2
	v_cmp_le_i32_e64 s[0:1], v1, v135
	v_exp_f32_e32 v4, v4
	v_fma_f32 v3, v32, v3, 0
	v_cndmask_b32_e64 v1, 0, v2, s[0:1]
	v_add_u32_e32 v2, 0xfffffcd0, v26
	v_cmp_le_i32_e64 s[0:1], v2, v135
	v_mul_f32_e32 v4, v32, v4
	v_sub_f32_e32 v5, v8, v33
	v_cndmask_b32_e64 v2, 0, v3, s[0:1]
	v_add_u32_e32 v3, 0xfffffce0, v26
	v_cmp_le_i32_e64 s[0:1], v3, v135
	v_exp_f32_e32 v5, v5
	v_sub_f32_e32 v8, v13, v33
	v_cndmask_b32_e64 v3, 0, v4, s[0:1]
	v_sub_f32_e32 v4, v6, v33
	v_exp_f32_e32 v4, v4
	v_add_f32_e32 v2, v3, v2
	v_add_u32_e32 v3, 0xfffffcf0, v26
	v_cmp_le_i32_e64 s[0:1], v3, v135
	v_mul_f32_e32 v4, v32, v4
	v_sub_f32_e32 v6, v9, v33
	v_cndmask_b32_e64 v3, 0, v4, s[0:1]
	v_sub_f32_e32 v4, v7, v33
	v_exp_f32_e32 v4, v4
	v_add_f32_e32 v2, v3, v2
	v_add_u32_e32 v3, 0xfffffd00, v26
	v_cmp_le_i32_e64 s[0:1], v3, v135
	v_mul_f32_e32 v4, v32, v4
	v_exp_f32_e32 v6, v6
	v_cndmask_b32_e64 v3, 0, v4, s[0:1]
	v_add_u32_e32 v4, 0xfffffd50, v26
	v_fma_f32 v5, v32, v5, 0
	v_cmp_le_i32_e64 s[0:1], v4, v135
	v_mul_f32_e32 v6, v32, v6
	v_sub_f32_e32 v7, v12, v33
	v_cndmask_b32_e64 v4, 0, v5, s[0:1]
	v_add_u32_e32 v5, 0xfffffd60, v26
	v_cmp_le_i32_e64 s[0:1], v5, v135
	v_exp_f32_e32 v7, v7
	v_exp_f32_e32 v8, v8
	v_cndmask_b32_e64 v5, 0, v6, s[0:1]
	v_sub_f32_e32 v6, v10, v33
	v_exp_f32_e32 v6, v6
	v_add_f32_e32 v4, v5, v4
	v_add_u32_e32 v5, 0xfffffd70, v26
	v_cmp_le_i32_e64 s[0:1], v5, v135
	v_mul_f32_e32 v6, v32, v6
	v_fma_f32 v7, v32, v7, 0
	v_cndmask_b32_e64 v5, 0, v6, s[0:1]
	v_sub_f32_e32 v6, v11, v33
	v_exp_f32_e32 v6, v6
	v_add_f32_e32 v4, v5, v4
	v_add_u32_e32 v5, 0xfffffd80, v26
	v_cmp_le_i32_e64 s[0:1], v5, v135
	v_mul_f32_e32 v6, v32, v6
	v_mul_f32_e32 v8, v32, v8
	v_cndmask_b32_e64 v5, 0, v6, s[0:1]
	v_add_u32_e32 v6, 0xfffffdd0, v26
	v_cmp_le_i32_e64 s[0:1], v6, v135
	v_add_f32_e32 v0, v1, v0
	ds_bpermute_b32 v1, v91, v1
	v_cndmask_b32_e64 v6, 0, v7, s[0:1]
	v_add_u32_e32 v7, 0xfffffde0, v26
	v_cmp_le_i32_e64 s[0:1], v7, v135
	v_add_f32_e32 v2, v3, v2
	ds_bpermute_b32 v3, v91, v3
	v_cndmask_b32_e64 v7, 0, v8, s[0:1]
	v_sub_f32_e32 v8, v14, v33
	v_exp_f32_e32 v8, v8
	v_add_f32_e32 v6, v7, v6
	v_add_u32_e32 v7, 0xfffffdf0, v26
	v_cmp_le_i32_e64 s[0:1], v7, v135
	v_mul_f32_e32 v8, v32, v8
	v_add_f32_e32 v4, v5, v4
	v_cndmask_b32_e64 v7, 0, v8, s[0:1]
	v_sub_f32_e32 v8, v15, v33
	v_exp_f32_e32 v8, v8
	v_add_f32_e32 v6, v7, v6
	v_add_u32_e32 v7, 0xfffffe00, v26
	v_cmp_le_i32_e64 s[0:1], v7, v135
	v_mul_f32_e32 v8, v32, v8
	ds_bpermute_b32 v5, v91, v5
	v_cndmask_b32_e64 v7, 0, v8, s[0:1]
	ds_bpermute_b32 v36, v91, v7
	v_add_f32_e32 v6, v7, v6
	s_waitcnt lgkmcnt(3)
	v_cndmask_b32_e32 v7, v1, v28, vcc
	v_add_f32_e32 v31, v7, v0
	s_waitcnt lgkmcnt(2)
	v_cndmask_b32_e32 v0, v3, v1, vcc
	v_add_f32_e32 v34, v0, v2
	s_waitcnt lgkmcnt(1)
	v_cndmask_b32_e32 v0, v5, v3, vcc
	v_add_f32_e32 v29, v0, v4
	s_waitcnt lgkmcnt(0)
	v_cndmask_b32_e32 v0, v36, v5, vcc
	v_add_f32_e32 v30, v0, v6
	ds_read_b128 v[0:3], v35 offset:4608
	s_waitcnt lgkmcnt(0)
	v_mfma_f32_32x32x16_bf16 v[0:15], v[0:3], v[64:67], 0
	v_add_u32_e32 v28, 0xfffffe50, v26
	v_cmp_le_i32_e64 s[0:1], v28, v135
	v_add_u32_e32 v28, 0xfffffe60, v26
	v_mfma_f32_32x32x16_bf16 v[0:15], v[38:41], v[68:71], v[0:15]
	ds_read_b128 v[38:41], v35 offset:4672
	s_waitcnt lgkmcnt(0)
	v_mfma_f32_32x32x16_bf16 v[0:15], v[38:41], v[72:75], v[0:15]
	ds_read_b128 v[38:41], v35 offset:4704
	s_waitcnt lgkmcnt(0)
; #define MFMA32(a, b, c) __builtin_amdgcn_mfma_f32_32x32x16_bf16((a), (b), (c), 0, 0, 0)
; DI float ex2(float x) { return __builtin_amdgcn_exp2f(x); }
; DI float xor32(float v) { return __shfl_xor(v, 32); }
; DI void task_nsa(const P& p, int layer, int task, bf16_t* sm, int dm) {
;     ...
;         for (int ks = 0; ks < 4; ++ks) {
;           bf16x8 kf = *(const bf16x8*)(Kl + (st * 32 + lr) * 72 + ks * 16 + lh * 8);
;           s = MFMA32(kf, q[ks], s);
;         }
;         float pq[4], pl[4], other[4];
; #pragma unroll
;         for (int g4 = 0; g4 < 4; ++g4) {
;           float sum = 0.f, last = 0.f;
; #pragma unroll
;           for (int e = 0; e < 4; ++e) {
;             const int cc = ct * 64 + st * 32 + 8 * g4 + 4 * lh + e;
;             const float pe = (16 * cc + 31 <= qp) ? ex2(s[4 * g4 + e] - m) * inv : 0.f;
;             sum += pe; last = pe;
;           }
;           pq[g4] = sum; pl[g4] = last;
;         }
; #pragma unroll
;         for (int g4 = 0; g4 < 4; ++g4) other[g4] = xor32(pl[g4]);
;         val[st][0] = pq[0] + (lh ? other[0] : carry);
;         val[st][1] = pq[1] + (lh ? other[1] : other[0]);
;         val[st][2] = pq[2] + (lh ? other[2] : other[1]);
;         val[st][3] = pq[3] + (lh ? other[3] : other[2]);
;         carry = other[3];
;       }
;       for (int w = 0; w < 4; ++w) {
;         if (hr == w) {
; #pragma unroll
;           for (int st = 0; st < 2; ++st)
; #pragma unroll
;             for (int g4 = 0; g4 < 4; ++g4) cbuf[(ct * 16 + st * 8 + 2 * g4 + lh) * 65 + ql] += val[st][g4];
;         }
;         __syncthreads();
;       }
	v_mfma_f32_32x32x16_bf16 v[0:15], v[38:41], v[76:79], v[0:15]
	s_nop 11
	v_sub_f32_e32 v0, v0, v33
	v_exp_f32_e32 v0, v0
	v_sub_f32_e32 v1, v1, v33
	v_exp_f32_e32 v1, v1
	v_sub_f32_e32 v2, v2, v33
	v_fma_f32 v0, v32, v0, 0
	v_exp_f32_e32 v2, v2
	v_cndmask_b32_e64 v0, 0, v0, s[0:1]
	v_mul_f32_e32 v1, v32, v1
	v_cmp_le_i32_e64 s[0:1], v28, v135
	v_mul_f32_e32 v2, v32, v2
	s_nop 0
	v_cndmask_b32_e64 v1, 0, v1, s[0:1]
	v_add_f32_e32 v0, v1, v0
	v_add_u32_e32 v1, 0xfffffe70, v26
	v_cmp_le_i32_e64 s[0:1], v1, v135
	s_nop 1
	v_cndmask_b32_e64 v1, 0, v2, s[0:1]
	v_sub_f32_e32 v2, v3, v33
	v_exp_f32_e32 v2, v2
	v_sub_f32_e32 v3, v4, v33
	v_exp_f32_e32 v3, v3
	v_add_f32_e32 v0, v1, v0
	v_add_u32_e32 v1, 0xfffffe80, v26
	v_sub_f32_e32 v4, v5, v33
	v_mul_f32_e32 v2, v32, v2
	v_cmp_le_i32_e64 s[0:1], v1, v135
	v_exp_f32_e32 v4, v4
	v_fma_f32 v3, v32, v3, 0
	v_cndmask_b32_e64 v1, 0, v2, s[0:1]
	v_add_u32_e32 v2, 0xfffffed0, v26
	v_cmp_le_i32_e64 s[0:1], v2, v135
	v_mul_f32_e32 v4, v32, v4
	v_sub_f32_e32 v5, v8, v33
	v_cndmask_b32_e64 v2, 0, v3, s[0:1]
	v_add_u32_e32 v3, 0xfffffee0, v26
	v_cmp_le_i32_e64 s[0:1], v3, v135
	v_exp_f32_e32 v5, v5
	v_sub_f32_e32 v8, v13, v33
	v_cndmask_b32_e64 v3, 0, v4, s[0:1]
	v_sub_f32_e32 v4, v6, v33
	v_exp_f32_e32 v4, v4
	v_add_f32_e32 v2, v3, v2
	v_add_u32_e32 v3, 0xfffffef0, v26
	v_cmp_le_i32_e64 s[0:1], v3, v135
	v_mul_f32_e32 v4, v32, v4
	v_sub_f32_e32 v6, v9, v33
	v_cndmask_b32_e64 v3, 0, v4, s[0:1]
	v_sub_f32_e32 v4, v7, v33
	v_exp_f32_e32 v4, v4
	v_add_f32_e32 v2, v3, v2
	v_add_u32_e32 v3, 0xffffff00, v26
	v_cmp_le_i32_e64 s[0:1], v3, v135
	v_mul_f32_e32 v4, v32, v4
	v_exp_f32_e32 v6, v6
	v_cndmask_b32_e64 v3, 0, v4, s[0:1]
	v_add_u32_e32 v4, 0xffffff50, v26
	v_fma_f32 v5, v32, v5, 0
	v_cmp_le_i32_e64 s[0:1], v4, v135
	v_mul_f32_e32 v6, v32, v6
	v_sub_f32_e32 v7, v12, v33
	v_cndmask_b32_e64 v4, 0, v5, s[0:1]
	v_add_u32_e32 v5, 0xffffff60, v26
	v_cmp_le_i32_e64 s[0:1], v5, v135
	v_exp_f32_e32 v7, v7
	v_exp_f32_e32 v8, v8
	v_cndmask_b32_e64 v5, 0, v6, s[0:1]
	v_sub_f32_e32 v6, v10, v33
	v_exp_f32_e32 v6, v6
	v_add_f32_e32 v4, v5, v4
	v_add_u32_e32 v5, 0xffffff70, v26
	v_cmp_le_i32_e64 s[0:1], v5, v135
	v_mul_f32_e32 v6, v32, v6
	v_fma_f32 v7, v32, v7, 0
	v_cndmask_b32_e64 v5, 0, v6, s[0:1]
	v_sub_f32_e32 v6, v11, v33
	v_exp_f32_e32 v6, v6
	v_add_f32_e32 v4, v5, v4
	v_add_u32_e32 v5, 0xffffff80, v26
	v_cmp_le_i32_e64 s[0:1], v5, v135
	v_mul_f32_e32 v6, v32, v6
	v_mul_f32_e32 v8, v32, v8
	v_cndmask_b32_e64 v5, 0, v6, s[0:1]
	v_add_f32_e32 v6, v5, v4
	v_subrev_u32_e32 v4, 48, v26
	v_cmp_le_i32_e64 s[0:1], v4, v135
	v_add_f32_e32 v0, v1, v0
	ds_bpermute_b32 v1, v91, v1
	v_cndmask_b32_e64 v4, 0, v7, s[0:1]
	v_subrev_u32_e32 v7, 32, v26
	v_cmp_le_i32_e64 s[0:1], v7, v135
	ds_bpermute_b32 v9, v91, v3
	ds_bpermute_b32 v5, v91, v5
	v_cndmask_b32_e64 v7, 0, v8, s[0:1]
	v_sub_f32_e32 v8, v14, v33
	v_exp_f32_e32 v8, v8
	v_add_f32_e32 v4, v7, v4
	v_add_u32_e32 v7, -16, v26
	v_cmp_le_i32_e64 s[0:1], v7, v135
	v_mul_f32_e32 v8, v32, v8
	v_add_f32_e32 v2, v3, v2
	v_cndmask_b32_e64 v7, 0, v8, s[0:1]
	v_add_f32_e32 v4, v7, v4
	v_sub_f32_e32 v7, v15, v33
	v_exp_f32_e32 v7, v7
	v_cmp_le_i32_e64 s[0:1], v26, v135
	s_waitcnt lgkmcnt(2)
	v_cndmask_b32_e32 v3, v1, v36, vcc
	v_add_f32_e32 v3, v3, v0
	v_mul_f32_e32 v7, v32, v7
	v_cndmask_b32_e64 v7, 0, v7, s[0:1]
	ds_bpermute_b32 v28, v91, v7
	s_waitcnt lgkmcnt(2)
	v_cndmask_b32_e32 v0, v9, v1, vcc
	v_add_f32_e32 v8, v7, v4
	v_add_f32_e32 v4, v0, v2
	s_waitcnt lgkmcnt(1)
	v_cndmask_b32_e32 v0, v5, v9, vcc
	s_waitcnt lgkmcnt(0)
	v_cndmask_b32_e32 v1, v28, v5, vcc
	v_add_f32_e32 v0, v0, v6
	v_add_f32_e32 v1, v1, v8
	v_add_u32_e32 v6, 0x400, v25
	v_add_u32_e32 v5, 0x800, v25
	v_add_u32_e32 v2, 0xc00, v25
	s_and_saveexec_b64 s[0:1], s[2:3]
	s_cbranch_execz .LBB0_678
	ds_read2_b32 v[140:141], v25 offset1:130
	ds_read2_b32 v[142:143], v6 offset0:4 offset1:134
	ds_read2_b32 v[144:145], v5 offset0:8 offset1:138
	ds_read2_b32 v[146:147], v2 offset0:12 offset1:142
	s_waitcnt lgkmcnt(0)
	v_add_f32_e32 v148, v31, v140
	v_add_f32_e32 v149, v34, v141
	v_add_f32_e32 v150, v29, v142
	v_add_f32_e32 v151, v30, v143
	v_add_f32_e32 v152, v3, v144
	v_add_f32_e32 v153, v4, v145
	v_add_f32_e32 v154, v0, v146
	v_add_f32_e32 v155, v1, v147
	ds_write2_b32 v25, v148, v149 offset1:130
	ds_write2_b32 v6, v150, v151 offset0:4 offset1:134
	ds_write2_b32 v5, v152, v153 offset0:8 offset1:138
	ds_write2_b32 v2, v154, v155 offset0:12 offset1:142
.LBB0_678:
	s_or_b64 exec, exec, s[0:1]
	s_waitcnt lgkmcnt(0)
	s_barrier
	s_and_saveexec_b64 s[0:1], s[4:5]
	s_cbranch_execz .LBB0_680
	ds_read2_b32 v[140:141], v25 offset1:130
	ds_read2_b32 v[142:143], v6 offset0:4 offset1:134
	ds_read2_b32 v[144:145], v5 offset0:8 offset1:138
	ds_read2_b32 v[146:147], v2 offset0:12 offset1:142
	s_waitcnt lgkmcnt(0)
	v_add_f32_e32 v148, v31, v140
	v_add_f32_e32 v149, v34, v141
	v_add_f32_e32 v150, v29, v142
	v_add_f32_e32 v151, v30, v143
	v_add_f32_e32 v152, v3, v144
	v_add_f32_e32 v153, v4, v145
	v_add_f32_e32 v154, v0, v146
	v_add_f32_e32 v155, v1, v147
	ds_write2_b32 v25, v148, v149 offset1:130
	ds_write2_b32 v6, v150, v151 offset0:4 offset1:134
	ds_write2_b32 v5, v152, v153 offset0:8 offset1:138
	ds_write2_b32 v2, v154, v155 offset0:12 offset1:142
.LBB0_680:
	s_or_b64 exec, exec, s[0:1]
	s_waitcnt lgkmcnt(0)
	s_barrier
	s_and_saveexec_b64 s[0:1], s[6:7]
	s_cbranch_execz .LBB0_682
	ds_read2_b32 v[140:141], v25 offset1:130
	ds_read2_b32 v[142:143], v6 offset0:4 offset1:134
	ds_read2_b32 v[144:145], v5 offset0:8 offset1:138
	ds_read2_b32 v[146:147], v2 offset0:12 offset1:142
	s_waitcnt lgkmcnt(0)
	v_add_f32_e32 v148, v31, v140
	v_add_f32_e32 v149, v34, v141
	v_add_f32_e32 v150, v29, v142
	v_add_f32_e32 v151, v30, v143
	v_add_f32_e32 v152, v3, v144
	v_add_f32_e32 v153, v4, v145
	v_add_f32_e32 v154, v0, v146
	v_add_f32_e32 v155, v1, v147
	ds_write2_b32 v25, v148, v149 offset1:130
	ds_write2_b32 v6, v150, v151 offset0:4 offset1:134
	ds_write2_b32 v5, v152, v153 offset0:8 offset1:138
	ds_write2_b32 v2, v154, v155 offset0:12 offset1:142
.LBB0_682:
	s_or_b64 exec, exec, s[0:1]
	s_waitcnt lgkmcnt(0)
	s_barrier
	s_and_saveexec_b64 s[0:1], s[8:9]
	s_cbranch_execz .LBB0_673
	ds_read2_b32 v[140:141], v25 offset1:130
	ds_read2_b32 v[142:143], v6 offset0:4 offset1:134
	ds_read2_b32 v[144:145], v5 offset0:8 offset1:138
	ds_read2_b32 v[146:147], v2 offset0:12 offset1:142
	s_waitcnt lgkmcnt(0)
	v_add_f32_e32 v148, v31, v140
	v_add_f32_e32 v149, v34, v141
	v_add_f32_e32 v150, v29, v142
	v_add_f32_e32 v151, v30, v143
	v_add_f32_e32 v152, v3, v144
	v_add_f32_e32 v153, v4, v145
	v_add_f32_e32 v154, v0, v146
	v_add_f32_e32 v155, v1, v147
	ds_write2_b32 v25, v148, v149 offset1:130
	ds_write2_b32 v6, v150, v151 offset0:4 offset1:134
	ds_write2_b32 v5, v152, v153 offset0:8 offset1:138
	ds_write2_b32 v2, v154, v155 offset0:12 offset1:142
	s_branch .LBB0_673
